# MLA loop: waves 4-7 run PV one half-tile behind waves 0-3 (two barriers per tile), next-tile LDS stores moved to iteration end
# baseline (speedup 1.0000x reference)
; DI float shx(float v, int mask) { const int l = lane_id(); return __int_as_float(__builtin_amdgcn_ds_bpermute((l ^ mask) << 2, __float_as_int(v))); }
; DI float bflo(unsigned v) { return __uint_as_float(v << 16); }
; DI float bfhi(unsigned v) { return __uint_as_float(v & 0xffff0000u); }
; DI void mla_phase(const Args& A, LAS unsigned char* lds, int i, const int wv) {
;     ...
;     for (int uid = blockIdx.x; uid < 2048; uid += gridDim.x) {
;         const int bh = (uid >> 8) * 8 + (uid & 7), qb = (uid >> 3) & 31, b = bh >> 3, head = bh & 7;
;         const size_t tq = (size_t)b * SEQ + qb * 256 + w * 32 + r32;
;         bf16x8 qf[6];
;         {
;             float qv[6][8]; float ss = 0.f;
; #pragma unroll
;             for (int s = 0; s < 6; ++s) { const u32x4 raw = *(const u32x4*)(QH + tq * 768 + head * 96 + 16 * s + 8 * h);
;                 qv[s][0] = bflo(raw.x); qv[s][1] = bfhi(raw.x); qv[s][2] = bflo(raw.y); qv[s][3] = bfhi(raw.y); qv[s][4] = bflo(raw.z); qv[s][5] = bfhi(raw.z); qv[s][6] = bflo(raw.w); qv[s][7] = bfhi(raw.w);
; #pragma unroll
;                 for (int j = 0; j < 8; ++j) ss += qv[s][j] * qv[s][j]; }
;             ss += shx(ss, 32);
;             const float rs = 1.0f / sqrtf(ss * (1.0f / 96.0f) + EPS);
; #pragma unroll
;             for (int s = 0; s < 6; ++s)
; #pragma unroll
;                 for (int j = 0; j < 8; ++j) qv[s][j] *= rs * qn[16 * s + 8 * h + j];
; #pragma unroll
;             for (int j = 0; j < 8; ++j) { const float c = ropeC[tq * 32 + 8 * h + j], sn = ropeC[tq * 32 + 16 + 8 * h + j]; const float lo = qv[4][j], hi = qv[5][j];
.LBB1_885:
	s_ashr_i32 s4, s13, 8
	s_lshl_b32 s6, s13, 5
	s_ashr_i32 s5, s4, 31
	s_and_b32 s6, s6, 0x1f00
	s_lshl_b64 s[2:3], s[4:5], 13
	v_add_u32_e32 v0, s6, v245
	v_lshl_add_u64 v[14:15], s[2:3], 0, v[0:1]
	v_readlane_b32 s2, v253, 25
	v_readlane_b32 s3, v253, 26
	s_and_b32 s26, s13, 7
	s_mul_i32 s6, s26, 0xc0
	v_mov_b64_e32 v[2:3], s[2:3]
	v_mad_u64_u32 v[2:3], s[2:3], v14, s87, v[2:3]
	v_mad_i32_i24 v3, v15, s87, v3
	s_mov_b32 s7, s76
	v_lshl_add_u64 v[2:3], v[2:3], 0, s[6:7]
	v_mov_b32_e32 v215, v1
	v_lshl_add_u64 v[2:3], v[2:3], 0, v[214:215]
	global_load_dwordx4 v[22:25], v[2:3], off offset:128
	global_load_dwordx4 v[26:29], v[2:3], off offset:160
	global_load_dwordx4 v[40:43], v[2:3], off offset:96
	global_load_dwordx4 v[44:47], v[2:3], off offset:64
	global_load_dwordx4 v[48:51], v[2:3], off offset:32
	global_load_dwordx4 v[52:55], v[2:3], off
	v_mbcnt_lo_u32_b32 v0, -1, 0
	v_mbcnt_hi_u32_b32 v0, -1, v0
	global_load_dwordx4 v[2:5], v[186:187], off offset:272
	global_load_dwordx4 v[6:9], v[186:187], off offset:256
	global_load_dwordx4 v[10:13], v[186:187], off offset:208
	global_load_dwordx4 v[18:21], v[186:187], off offset:192
	global_load_dwordx4 v[56:59], v[186:187], off offset:144
	global_load_dwordx4 v[60:63], v[186:187], off offset:128
	global_load_dwordx4 v[64:67], v[186:187], off offset:80
	global_load_dwordx4 v[68:71], v[186:187], off offset:64
	v_lshlrev_b32_e32 v0, 2, v0
	v_xor_b32_e32 v0, 0x80, v0
	v_mad_u64_u32 v[220:221], s[2:3], v14, s87, 0
	v_mad_i32_i24 v221, v15, s87, v221
	v_lshlrev_b64 v[14:15], 7, v[14:15]
	s_and_b32 s24, s12, 7
	s_lshl_b32 s25, s24, 7
	v_readlane_b32 s8, v253, 27
	v_mov_b32_e32 v217, v1
	s_mov_b32 s7, 0
	v_mov_b32_e32 v181, 0
	s_waitcnt vmcnt(13)
	v_lshlrev_b32_e32 v80, 16, v22
	v_and_b32_e32 v81, 0xffff0000, v22
	s_waitcnt vmcnt(11)
	v_lshlrev_b32_e32 v82, 16, v43
	v_and_b32_e32 v83, 0xffff0000, v43
	v_lshlrev_b32_e32 v84, 16, v42
	s_waitcnt vmcnt(8)
	v_lshlrev_b32_e32 v138, 16, v52
	v_and_b32_e32 v139, 0xffff0000, v52
	v_lshlrev_b32_e32 v134, 16, v53
	v_and_b32_e32 v135, 0xffff0000, v53
	v_pk_mul_f32 v[52:53], v[138:139], v[138:139]
	v_pk_mul_f32 v[136:137], v[134:135], v[134:135]
	v_add_f32_e32 v52, v52, v53
	v_lshlrev_b32_e32 v132, 16, v54
	v_and_b32_e32 v133, 0xffff0000, v54
	v_add_f32_e32 v52, v136, v52
	v_lshlrev_b32_e32 v128, 16, v55
	v_and_b32_e32 v129, 0xffff0000, v55
	v_pk_mul_f32 v[54:55], v[132:133], v[132:133]
	v_add_f32_e32 v52, v137, v52
	v_add_f32_e32 v52, v54, v52
	v_and_b32_e32 v85, 0xffff0000, v42
	v_lshlrev_b32_e32 v86, 16, v41
	v_and_b32_e32 v87, 0xffff0000, v41
	v_lshlrev_b32_e32 v88, 16, v40
	v_and_b32_e32 v89, 0xffff0000, v40
	v_lshlrev_b32_e32 v90, 16, v47
	v_and_b32_e32 v91, 0xffff0000, v47
	v_lshlrev_b32_e32 v92, 16, v46
	v_and_b32_e32 v93, 0xffff0000, v46
	v_lshlrev_b32_e32 v94, 16, v45
	v_and_b32_e32 v95, 0xffff0000, v45
	v_lshlrev_b32_e32 v96, 16, v44
	v_and_b32_e32 v97, 0xffff0000, v44
	v_pk_mul_f32 v[130:131], v[128:129], v[128:129]
	global_load_dwordx4 v[40:43], v[186:187], off offset:16
	global_load_dwordx4 v[44:47], v[186:187], off
	v_add_f32_e32 v52, v55, v52
	v_lshlrev_b32_e32 v126, 16, v48
	v_and_b32_e32 v127, 0xffff0000, v48
	v_add_f32_e32 v52, v130, v52
	v_lshlrev_b32_e32 v122, 16, v49
	v_and_b32_e32 v123, 0xffff0000, v49
	v_pk_mul_f32 v[48:49], v[126:127], v[126:127]
	v_add_f32_e32 v52, v131, v52
	v_add_f32_e32 v48, v48, v52
	v_pk_mul_f32 v[124:125], v[122:123], v[122:123]
	v_add_f32_e32 v48, v49, v48
	v_lshlrev_b32_e32 v100, 16, v50
	v_and_b32_e32 v101, 0xffff0000, v50
	v_add_f32_e32 v48, v124, v48
	v_pk_mul_f32 v[120:121], v[100:101], v[100:101]
	v_add_f32_e32 v48, v125, v48
	v_lshlrev_b32_e32 v98, 16, v51
	v_and_b32_e32 v99, 0xffff0000, v51
	v_add_f32_e32 v48, v120, v48
	v_pk_mul_f32 v[118:119], v[98:99], v[98:99]
	v_add_f32_e32 v48, v121, v48
	v_add_f32_e32 v48, v118, v48
	v_pk_mul_f32 v[116:117], v[96:97], v[96:97]
	v_add_f32_e32 v48, v119, v48
	v_add_f32_e32 v48, v116, v48
	v_pk_mul_f32 v[114:115], v[94:95], v[94:95]
	v_add_f32_e32 v48, v117, v48
	v_add_f32_e32 v48, v114, v48
	v_pk_mul_f32 v[112:113], v[92:93], v[92:93]
	v_add_f32_e32 v48, v115, v48
	v_add_f32_e32 v48, v112, v48
	v_pk_mul_f32 v[110:111], v[90:91], v[90:91]
	v_add_f32_e32 v48, v113, v48
	v_add_f32_e32 v48, v110, v48
	v_pk_mul_f32 v[108:109], v[88:89], v[88:89]
	v_add_f32_e32 v48, v111, v48
	v_add_f32_e32 v48, v108, v48
	v_pk_mul_f32 v[106:107], v[86:87], v[86:87]
	v_add_f32_e32 v48, v109, v48
	v_add_f32_e32 v48, v106, v48
	v_pk_mul_f32 v[104:105], v[84:85], v[84:85]
	v_add_f32_e32 v48, v107, v48
	v_add_f32_e32 v48, v104, v48
	v_pk_mul_f32 v[102:103], v[82:83], v[82:83]
	v_add_f32_e32 v48, v105, v48
	v_add_f32_e32 v48, v102, v48
	v_pk_mul_f32 v[72:73], v[80:81], v[80:81]
	v_add_f32_e32 v48, v103, v48
	v_lshlrev_b32_e32 v78, 16, v23
	v_and_b32_e32 v79, 0xffff0000, v23
	v_add_f32_e32 v48, v72, v48
	v_lshlrev_b32_e32 v30, 16, v29
	v_and_b32_e32 v31, 0xffff0000, v29
	v_lshlrev_b32_e32 v32, 16, v28
	v_and_b32_e32 v33, 0xffff0000, v28
	v_pk_mul_f32 v[28:29], v[78:79], v[78:79]
	v_add_f32_e32 v48, v73, v48
	v_lshlrev_b32_e32 v76, 16, v24
	v_and_b32_e32 v77, 0xffff0000, v24
	v_add_f32_e32 v28, v28, v48
	v_lshlrev_b32_e32 v34, 16, v25
	v_and_b32_e32 v35, 0xffff0000, v25
	v_pk_mul_f32 v[24:25], v[76:77], v[76:77]
	v_add_f32_e32 v28, v29, v28
	v_add_f32_e32 v24, v24, v28
	v_pk_mul_f32 v[16:17], v[34:35], v[34:35]
	v_add_f32_e32 v24, v25, v24
	v_lshlrev_b32_e32 v38, 16, v26
	v_and_b32_e32 v39, 0xffff0000, v26
	v_add_f32_e32 v16, v16, v24
	v_pk_mul_f32 v[74:75], v[38:39], v[38:39]
	v_add_f32_e32 v16, v17, v16
	v_lshlrev_b32_e32 v36, 16, v27
	v_and_b32_e32 v37, 0xffff0000, v27
	v_add_f32_e32 v16, v74, v16
	v_pk_mul_f32 v[50:51], v[36:37], v[36:37]
	v_add_f32_e32 v16, v75, v16
	v_add_f32_e32 v16, v50, v16
	v_pk_mul_f32 v[26:27], v[32:33], v[32:33]
	v_add_f32_e32 v16, v51, v16
	v_add_f32_e32 v16, v26, v16
	v_pk_mul_f32 v[22:23], v[30:31], v[30:31]
	v_add_f32_e32 v16, v27, v16
	v_add_f32_e32 v16, v22, v16
	v_add_f32_e32 v16, v23, v16
	ds_bpermute_b32 v0, v0, v16
	v_lshl_add_u64 v[72:73], v[184:185], 0, v[14:15]
	s_waitcnt lgkmcnt(0)
; DI unsigned cvtpk(float lo, float hi) { typedef __bf16 b2 __attribute__((ext_vector_type(2))); f32x2 v = {lo, hi}; b2 b = __builtin_convertvector(v, b2); return __builtin_bit_cast(unsigned, b); }
; DI f32x16 zero16() { f32x16 z; for (int i = 0; i < 16; ++i) z[i] = 0.f; return z; }
; DI void mla_phase(const Args& A, LAS unsigned char* lds, int i, const int wv) {
;     ...
;             const float rs = 1.0f / sqrtf(ss * (1.0f / 96.0f) + EPS);
; #pragma unroll
;             for (int s = 0; s < 6; ++s)
; #pragma unroll
;                 for (int j = 0; j < 8; ++j) qv[s][j] *= rs * qn[16 * s + 8 * h + j];
; #pragma unroll
;             for (int j = 0; j < 8; ++j) { const float c = ropeC[tq * 32 + 8 * h + j], sn = ropeC[tq * 32 + 16 + 8 * h + j]; const float lo = qv[4][j], hi = qv[5][j];
;                 qv[4][j] = lo * c - hi * sn; qv[5][j] = hi * c + lo * sn; }
;             const float sc = 0.10206207261596577f * LOG2E;
; #pragma unroll
;             for (int s = 0; s < 6; ++s) { u32x4 pk; pk.x = cvtpk(qv[s][0] * sc, qv[s][1] * sc); pk.y = cvtpk(qv[s][2] * sc, qv[s][3] * sc); pk.z = cvtpk(qv[s][4] * sc, qv[s][5] * sc); pk.w = cvtpk(qv[s][6] * sc, qv[s][7] * sc); qf[s] = __builtin_bit_cast(bf16x8, pk); }
;         }
;         const bf16_t* Kg = KH + ((size_t)b * SEQ) * 768 + head * 96; const bf16_t* Vg = VH + ((size_t)b * SEQ) * 512 + head * 64;
;         u32x4 kq[3], vq[2];
;     ...
;         constexpr int KB2 = 128 * 208, VB2 = 128 * 144, TB = KB2 + VB2;
;         float mrow = 0.f, l = 0.f; f32x16 o[2]; o[0] = zero16(); o[1] = zero16(); f32x16 negm = zero16();
;         MLA_LD(0); MLA_ST(0);
	v_add_f32_e32 v0, v16, v0
	v_fmamk_f32 v0, v0, 0x3c2aaaab, v232
	v_mul_f32_e32 v14, 0x4f800000, v0
	v_cmp_gt_f32_e32 vcc, s91, v0
	s_nop 1
	v_cndmask_b32_e32 v0, v0, v14, vcc
	v_sqrt_f32_e32 v26, v0
	global_load_dwordx4 v[48:51], v[186:187], off offset:336
	global_load_dwordx4 v[52:55], v[186:187], off offset:320
	global_load_dwordx4 v[14:17], v[72:73], off offset:16
	global_load_dwordx4 v[22:25], v[72:73], off
	v_add_u32_e32 v27, -1, v26
	v_fma_f32 v28, -v27, v26, v0
	v_cmp_ge_f32_e64 s[2:3], 0, v28
	v_add_u32_e32 v28, 1, v26
	s_nop 0
	v_cndmask_b32_e64 v27, v26, v27, s[2:3]
	v_fma_f32 v26, -v28, v26, v0
	v_cmp_lt_f32_e64 s[2:3], 0, v26
	s_nop 1
	v_cndmask_b32_e64 v26, v27, v28, s[2:3]
	v_mul_f32_e32 v27, 0x37800000, v26
	v_cndmask_b32_e32 v26, v26, v27, vcc
	v_cmp_class_f32_e32 vcc, v0, v233
	s_nop 1
	v_cndmask_b32_e32 v0, v26, v0, vcc
	v_div_scale_f32 v102, s[2:3], v0, v0, 1.0
	v_rcp_f32_e32 v103, v102
	global_load_dwordx4 v[26:29], v[72:73], off offset:80
	s_nop 0
	global_load_dwordx4 v[72:75], v[72:73], off offset:64
	s_mul_i32 s3, s4, 0xc00000
	s_mul_hi_i32 s2, s4, 0xc00000
	v_fma_f32 v104, -v102, v103, 1.0
	v_fmac_f32_e32 v103, v104, v103
	v_div_scale_f32 v104, vcc, 1.0, v0, 1.0
	v_mul_f32_e32 v105, v104, v103
	v_fma_f32 v106, -v102, v105, v104
	v_fmac_f32_e32 v105, v106, v103
	v_fma_f32 v102, -v102, v105, v104
	s_add_u32 s3, s8, s3
	v_readlane_b32 s8, v253, 28
	v_div_fmas_f32 v102, v102, v103, v105
	s_addc_u32 s2, s8, s2
	v_div_fixup_f32 v0, v102, v0, 1.0
	s_add_u32 s28, s3, s6
	s_waitcnt vmcnt(15)
	v_pk_mul_f32 v[2:3], v[2:3], v[0:1] op_sel_hi:[1,0]
	s_addc_u32 s29, s2, 0
	s_lshl_b64 s[2:3], s[4:5], 23
	s_lshl_b32 s5, s26, 6
	v_readlane_b32 s6, v253, 29
	s_waitcnt vmcnt(14)
	v_pk_mul_f32 v[8:9], v[8:9], v[0:1] op_sel_hi:[1,0]
	v_pk_mul_f32 v[2:3], v[2:3], v[76:77]
	v_lshl_add_u64 v[76:77], s[28:29], 0, v[188:189]
	s_add_u32 s6, s6, s2
	v_readlane_b32 s8, v253, 30
	s_waitcnt vmcnt(6)
	v_pk_mul_f32 v[46:47], v[46:47], v[0:1] op_sel_hi:[1,0]
	v_pk_mul_f32 v[40:41], v[40:41], v[0:1] op_sel_hi:[1,0]
	v_pk_mul_f32 v[42:43], v[42:43], v[0:1] op_sel_hi:[1,0]
	v_pk_mul_f32 v[8:9], v[8:9], v[78:79]
	v_lshl_add_u64 v[76:77], v[190:191], 1, v[76:77]
	v_lshl_add_u64 v[78:79], s[28:29], 0, v[192:193]
	s_addc_u32 s8, s8, s3
	s_lshl_b32 s9, s26, 7
	v_pk_mul_f32 v[46:47], v[46:47], v[134:135]
	v_pk_mul_f32 v[40:41], v[40:41], v[132:133]
	v_pk_mul_f32 v[42:43], v[42:43], v[128:129]
	v_lshl_add_u64 v[78:79], v[194:195], 1, v[78:79]
	global_load_dwordx4 v[128:131], v[76:77], off
	global_load_dwordx4 v[132:135], v[78:79], off
	v_lshl_add_u64 v[76:77], s[28:29], 0, v[196:197]
	s_add_u32 s26, s6, s9
	v_pk_mul_f32 v[44:45], v[44:45], v[0:1] op_sel_hi:[1,0]
	v_lshl_add_u64 v[76:77], v[198:199], 1, v[76:77]
	s_addc_u32 s27, s8, 0
	v_pk_mul_f32 v[44:45], v[44:45], v[138:139]
	global_load_dwordx4 v[136:139], v[76:77], off
	v_lshl_add_u64 v[76:77], s[26:27], 0, v[216:217]
	v_lshl_add_u64 v[78:79], v[76:77], 0, v[200:201]
	global_load_dwordx4 v[140:143], v[78:79], off
	v_lshl_add_u64 v[76:77], v[76:77], 0, v[202:203]
	global_load_dwordx4 v[144:147], v[76:77], off
	v_pk_mul_f32 v[10:11], v[10:11], v[0:1] op_sel_hi:[1,0]
	v_pk_mul_f32 v[4:5], v[4:5], v[0:1] op_sel_hi:[1,0]
	v_pk_mul_f32 v[10:11], v[10:11], v[84:85]
	v_pk_mul_f32 v[12:13], v[12:13], v[0:1] op_sel_hi:[1,0]
	v_pk_mul_f32 v[4:5], v[4:5], v[34:35]
	s_waitcnt vmcnt(9)
	v_pk_mul_f32 v[34:35], v[52:53], v[0:1] op_sel_hi:[1,0]
	s_mov_b32 s6, 0x3e16c740
	v_pk_mul_f32 v[12:13], v[12:13], v[82:83]
	v_pk_mul_f32 v[34:35], v[34:35], v[38:39]
	v_pk_mul_f32 v[38:39], v[54:55], v[0:1] op_sel_hi:[1,0]
	v_pk_mul_f32 v[10:11], v[10:11], s[6:7] op_sel_hi:[1,0]
	v_pk_mul_f32 v[6:7], v[6:7], v[0:1] op_sel_hi:[1,0]
	v_pk_mul_f32 v[36:37], v[38:39], v[36:37]
	v_pk_mul_f32 v[38:39], v[48:49], v[0:1] op_sel_hi:[1,0]
	v_cvt_pk_bf16_f32 v162, v10, v11
	v_pk_mul_f32 v[10:11], v[12:13], s[6:7] op_sel_hi:[1,0]
	v_pk_mul_f32 v[6:7], v[6:7], v[80:81]
	v_pk_mul_f32 v[32:33], v[38:39], v[32:33]
	v_pk_mul_f32 v[38:39], v[50:51], v[0:1] op_sel_hi:[1,0]
	v_cvt_pk_bf16_f32 v163, v10, v11
	v_pk_mul_f32 v[30:31], v[38:39], v[30:31]
	v_pk_mul_f32 v[68:69], v[68:69], v[0:1] op_sel_hi:[1,0]
	v_pk_mul_f32 v[40:41], v[40:41], s[6:7] op_sel_hi:[1,0]
	v_pk_mul_f32 v[68:69], v[68:69], v[126:127]
	v_pk_mul_f32 v[70:71], v[70:71], v[0:1] op_sel_hi:[1,0]
	v_cvt_pk_bf16_f32 v150, v40, v41
	v_pk_mul_f32 v[40:41], v[42:43], s[6:7] op_sel_hi:[1,0]
	s_waitcnt vmcnt(6)
	v_pk_mul_f32 v[50:51], v[2:3], v[26:27]
	s_waitcnt vmcnt(5)
; DI unsigned cvtpk(float lo, float hi) { typedef __bf16 b2 __attribute__((ext_vector_type(2))); f32x2 v = {lo, hi}; b2 b = __builtin_convertvector(v, b2); return __builtin_bit_cast(unsigned, b); }
; DI f32x16 zero16() { f32x16 z; for (int i = 0; i < 16; ++i) z[i] = 0.f; return z; }
; DI void mla_phase(const Args& A, LAS unsigned char* lds, int i, const int wv) {
;     ...
;             for (int j = 0; j < 8; ++j) { const float c = ropeC[tq * 32 + 8 * h + j], sn = ropeC[tq * 32 + 16 + 8 * h + j]; const float lo = qv[4][j], hi = qv[5][j];
;                 qv[4][j] = lo * c - hi * sn; qv[5][j] = hi * c + lo * sn; }
;             const float sc = 0.10206207261596577f * LOG2E;
; #pragma unroll
;             for (int s = 0; s < 6; ++s) { u32x4 pk; pk.x = cvtpk(qv[s][0] * sc, qv[s][1] * sc); pk.y = cvtpk(qv[s][2] * sc, qv[s][3] * sc); pk.z = cvtpk(qv[s][4] * sc, qv[s][5] * sc); pk.w = cvtpk(qv[s][6] * sc, qv[s][7] * sc); qf[s] = __builtin_bit_cast(bf16x8, pk); }
;         }
;         const bf16_t* Kg = KH + ((size_t)b * SEQ) * 768 + head * 96; const bf16_t* Vg = VH + ((size_t)b * SEQ) * 512 + head * 64;
;         u32x4 kq[3], vq[2];
;     ...
;         constexpr int KB2 = 128 * 208, VB2 = 128 * 144, TB = KB2 + VB2;
;         float mrow = 0.f, l = 0.f; f32x16 o[2]; o[0] = zero16(); o[1] = zero16(); f32x16 negm = zero16();
;         MLA_LD(0); MLA_ST(0);
;         __syncthreads();
	v_pk_mul_f32 v[10:11], v[34:35], v[72:73]
	v_pk_mul_f32 v[38:39], v[72:73], v[6:7]
	v_pk_fma_f32 v[6:7], v[22:23], v[6:7], v[10:11] neg_lo:[0,0,1] neg_hi:[0,0,1]
	v_pk_mul_f32 v[70:71], v[70:71], v[122:123]
	v_pk_mul_f32 v[6:7], v[6:7], s[6:7] op_sel_hi:[1,0]
	v_pk_mul_f32 v[64:65], v[64:65], v[0:1] op_sel_hi:[1,0]
	v_cvt_pk_bf16_f32 v164, v6, v7
	v_pk_mul_f32 v[6:7], v[36:37], v[74:75]
	v_pk_fma_f32 v[38:39], v[22:23], v[34:35], v[38:39]
	v_pk_fma_f32 v[6:7], v[8:9], v[24:25], v[6:7] neg_lo:[0,0,1] neg_hi:[0,0,1]
	v_pk_mul_f32 v[48:49], v[8:9], v[74:75]
	v_pk_mul_f32 v[6:7], v[6:7], s[6:7] op_sel_hi:[1,0]
	v_cvt_pk_bf16_f32 v151, v40, v41
	v_cvt_pk_bf16_f32 v165, v6, v7
	v_pk_mul_f32 v[6:7], v[32:33], v[26:27]
	v_pk_mul_f32 v[40:41], v[68:69], s[6:7] op_sel_hi:[1,0]
	v_pk_fma_f32 v[2:3], v[2:3], v[14:15], v[6:7] neg_lo:[0,0,1] neg_hi:[0,0,1]
	v_pk_mul_f32 v[64:65], v[64:65], v[100:101]
	v_pk_mul_f32 v[2:3], v[2:3], s[6:7] op_sel_hi:[1,0]
	v_pk_mul_f32 v[66:67], v[66:67], v[0:1] op_sel_hi:[1,0]
	v_cvt_pk_bf16_f32 v166, v2, v3
	v_pk_mul_f32 v[2:3], v[30:31], v[28:29]
	v_pk_fma_f32 v[48:49], v[36:37], v[24:25], v[48:49]
	v_pk_fma_f32 v[2:3], v[4:5], v[16:17], v[2:3] neg_lo:[0,0,1] neg_hi:[0,0,1]
	v_cvt_pk_bf16_f32 v152, v40, v41
	v_pk_mul_f32 v[2:3], v[2:3], s[6:7] op_sel_hi:[1,0]
	v_pk_mul_f32 v[40:41], v[70:71], s[6:7] op_sel_hi:[1,0]
	v_cvt_pk_bf16_f32 v167, v2, v3
	v_pk_mul_f32 v[2:3], v[38:39], s[6:7] op_sel_hi:[1,0]
	v_pk_mul_f32 v[66:67], v[66:67], v[98:99]
	v_pk_mul_f32 v[60:61], v[60:61], v[0:1] op_sel_hi:[1,0]
	v_pk_mul_f32 v[62:63], v[62:63], v[0:1] op_sel_hi:[1,0]
	v_pk_mul_f32 v[56:57], v[56:57], v[0:1] op_sel_hi:[1,0]
	v_pk_mul_f32 v[58:59], v[58:59], v[0:1] op_sel_hi:[1,0]
	v_pk_mul_f32 v[18:19], v[18:19], v[0:1] op_sel_hi:[1,0]
	v_pk_mul_f32 v[20:21], v[20:21], v[0:1] op_sel_hi:[1,0]
	v_pk_fma_f32 v[50:51], v[32:33], v[14:15], v[50:51]
	v_pk_mul_f32 v[52:53], v[4:5], v[28:29]
	v_cvt_pk_bf16_f32 v153, v40, v41
	v_pk_mul_f32 v[40:41], v[64:65], s[6:7] op_sel_hi:[1,0]
	v_cvt_pk_bf16_f32 v168, v2, v3
	v_pk_mul_f32 v[2:3], v[48:49], s[6:7] op_sel_hi:[1,0]
	v_add_u32_e32 v0, v247, v175
	v_pk_mul_f32 v[60:61], v[60:61], v[96:97]
	v_pk_fma_f32 v[52:53], v[30:31], v[16:17], v[52:53]
	v_cvt_pk_bf16_f32 v154, v40, v41
	v_pk_mul_f32 v[40:41], v[66:67], s[6:7] op_sel_hi:[1,0]
	v_cvt_pk_bf16_f32 v169, v2, v3
	v_pk_mul_f32 v[2:3], v[50:51], s[6:7] op_sel_hi:[1,0]
	s_waitcnt vmcnt(4)
	ds_write_b128 v240, v[128:131]
	s_waitcnt vmcnt(3)
	ds_write_b128 v241, v[132:135]
	s_waitcnt vmcnt(2)
	ds_write_b128 v180, v[136:139]
	s_waitcnt vmcnt(1)
	ds_write_b128 v0, v[140:143] offset:26624
	v_add_u32_e32 v0, v247, v234
	v_pk_mul_f32 v[62:63], v[62:63], v[94:95]
	v_cvt_pk_bf16_f32 v155, v40, v41
	v_pk_mul_f32 v[40:41], v[60:61], s[6:7] op_sel_hi:[1,0]
	v_cvt_pk_bf16_f32 v170, v2, v3
	v_pk_mul_f32 v[2:3], v[52:53], s[6:7] op_sel_hi:[1,0]
	s_waitcnt vmcnt(0)
	ds_write_b128 v0, v[144:147] offset:26624
	s_or_b32 s2, s2, s25
	v_mov_b32_e32 v0, 0xc00000
	v_pk_mul_f32 v[56:57], v[56:57], v[92:93]
	v_pk_mul_f32 v[18:19], v[18:19], v[88:89]
	v_cvt_pk_bf16_f32 v156, v40, v41
	v_pk_mul_f32 v[40:41], v[62:63], s[6:7] op_sel_hi:[1,0]
	v_cvt_pk_bf16_f32 v171, v2, v3
	v_lshl_add_u64 v[222:223], s[2:3], 0, v[204:205]
	v_lshl_add_u64 v[224:225], s[2:3], 0, v[206:207]
	v_mad_i64_i32 v[2:3], s[2:3], s4, v0, v[208:209]
	v_mov_b32_e32 v4, 0xc0
	v_pk_mul_f32 v[58:59], v[58:59], v[90:91]
	v_pk_mul_f32 v[20:21], v[20:21], v[86:87]
	v_pk_mul_f32 v[44:45], v[44:45], s[6:7] op_sel_hi:[1,0]
	v_cvt_pk_bf16_f32 v157, v40, v41
	v_pk_mul_f32 v[40:41], v[56:57], s[6:7] op_sel_hi:[1,0]
	v_pk_mul_f32 v[18:19], v[18:19], s[6:7] op_sel_hi:[1,0]
	v_mad_u64_u32 v[226:227], s[2:3], s24, v4, v[2:3]
	v_mad_i64_i32 v[2:3], s[2:3], s4, v0, v[210:211]
	v_cvt_pk_bf16_f32 v148, v44, v45
	v_pk_mul_f32 v[44:45], v[46:47], s[6:7] op_sel_hi:[1,0]
	v_cvt_pk_bf16_f32 v158, v40, v41
	v_pk_mul_f32 v[40:41], v[58:59], s[6:7] op_sel_hi:[1,0]
	v_cvt_pk_bf16_f32 v160, v18, v19
	v_pk_mul_f32 v[18:19], v[20:21], s[6:7] op_sel_hi:[1,0]
	v_mad_u64_u32 v[228:229], s[2:3], s24, v4, v[2:3]
	v_mad_i64_i32 v[2:3], s[2:3], s4, v0, v[212:213]
	v_mov_b32_e32 v14, v1
	v_mov_b32_e32 v15, v1
	v_cvt_pk_bf16_f32 v149, v44, v45
	v_cvt_pk_bf16_f32 v159, v40, v41
	v_cvt_pk_bf16_f32 v161, v18, v19
	v_mad_u64_u32 v[230:231], s[2:3], s24, v4, v[2:3]
	v_mov_b32_e32 v0, v1
	v_mov_b32_e32 v2, v1
	v_mov_b32_e32 v3, v1
	v_mov_b32_e32 v4, v1
	v_mov_b32_e32 v5, v1
	v_mov_b32_e32 v6, v1
	v_mov_b32_e32 v7, v1
	v_mov_b32_e32 v8, v1
	v_mov_b32_e32 v9, v1
	v_mov_b32_e32 v10, v1
	v_mov_b32_e32 v11, v1
	v_mov_b32_e32 v12, v1
	v_mov_b32_e32 v13, v1
	v_mov_b64_e32 v[30:31], v[14:15]
	v_mov_b64_e32 v[46:47], v[14:15]
	v_mov_b64_e32 v[28:29], v[12:13]
	v_mov_b64_e32 v[26:27], v[10:11]
	v_mov_b64_e32 v[24:25], v[8:9]
	v_mov_b64_e32 v[22:23], v[6:7]
	v_mov_b64_e32 v[20:21], v[4:5]
	v_mov_b64_e32 v[18:19], v[2:3]
	v_mov_b64_e32 v[16:17], v[0:1]
	v_mov_b64_e32 v[44:45], v[12:13]
	v_mov_b64_e32 v[42:43], v[10:11]
	v_mov_b64_e32 v[40:41], v[8:9]
	v_mov_b64_e32 v[38:39], v[6:7]
	v_mov_b64_e32 v[36:37], v[4:5]
	v_mov_b64_e32 v[34:35], v[2:3]
	v_mov_b64_e32 v[32:33], v[0:1]
	v_mov_b32_e32 v0, 0
	v_mov_b32_e32 v48, 0
	v_mov_b32_e32 v49, v181
	v_mov_b32_e32 v50, v181
	v_mov_b32_e32 v51, v181
	v_mov_b32_e32 v52, v181
	v_mov_b32_e32 v53, v181
	v_mov_b32_e32 v54, v181
	v_mov_b32_e32 v55, v181
	v_mov_b32_e32 v56, v181
	v_mov_b32_e32 v57, v181
	v_mov_b32_e32 v58, v181
	v_mov_b32_e32 v59, v181
	v_mov_b32_e32 v60, v181
	v_mov_b32_e32 v61, v181
	v_mov_b32_e32 v62, v181
	v_mov_b32_e32 v63, v181
	s_waitcnt lgkmcnt(0)
	s_barrier
	v_readlane_b32 s2, v253, 18
	s_cmp_ge_u32 s2, 0x100
	s_cbranch_scc1 .Lmla_late_top

; #define LAS __attribute__((address_space(3)))
; #define MFMA32(a, b, c) __builtin_amdgcn_mfma_f32_32x32x16_bf16((a), (b), (c), 0, 0, 0)
; DI s16x4 trread(LAS const char* p) { return __builtin_bit_cast(s16x4, __builtin_amdgcn_ds_read_tr16_b64_v4i16((LAS v4i16_t*)p)); }
; DI bf16x8 cat8(s16x4 lo, s16x4 hi) { return __builtin_shufflevector(lo, hi, 0, 1, 2, 3, 4, 5, 6, 7); }
; DI void mla_phase(const Args& A, LAS unsigned char* lds, int i, const int wv) {
;     ...
;             if (__any(mx > 8.0f)) {
;                 const float dl = fmaxf(mx, 0.f), alpha = __builtin_amdgcn_exp2f(-dl); mrow += dl; l *= alpha;
; #pragma unroll
;                 for (int rg = 0; rg < 16; ++rg) { p[0][rg] -= dl; p[1][rg] -= dl; p[2][rg] -= dl; p[3][rg] -= dl; o[0][rg] *= alpha; o[1][rg] *= alpha; negm[rg] = -mrow; }
;             }
;             float ls = 0.f;
; #pragma unroll
;             for (int kt = 0; kt < 4; ++kt)
; #pragma unroll
;                 for (int rg = 0; rg < 16; ++rg) { p[kt][rg] = __builtin_amdgcn_exp2f(p[kt][rg]); ls += p[kt][rg]; }
;             l += ls;
; #pragma unroll
;             for (int kt = 0; kt < 4; ++kt)
; #pragma unroll
;                 for (int s = 0; s < 2; ++s) { const bf16x8 pb = pack8(p[kt], s);
; #pragma unroll
;                     for (int dt = 0; dt < 2; ++dt) { LAS const char* ad = (LAS const char*)vbp + (32 * kt + 16 * s + 4 * h + q_) * 144 + (32 * dt + 16 * blk) * 2 + 8 * p_;
;                         const bf16x8 va = cat8(trread(ad), trread(ad + 8 * 144)); o[dt] = MFMA32(va, pb, o[dt]); } }
.Lmla_a_norescale:
	s_barrier
	v_exp_f32_e32 v112, v112
	v_exp_f32_e32 v113, v113
	v_exp_f32_e32 v114, v114
	v_exp_f32_e32 v115, v115
	v_exp_f32_e32 v116, v116
	v_exp_f32_e32 v117, v117
	v_exp_f32_e32 v118, v118
	v_exp_f32_e32 v119, v119
	v_add_f32_e32 v14, v112, v113
	v_add_f32_e32 v15, v114, v115
	v_add_f32_e32 v14, v14, v116
	v_add_f32_e32 v15, v15, v117
	v_add_f32_e32 v14, v14, v118
	v_add_f32_e32 v15, v15, v119
	v_cvt_pk_bf16_f32 v10, v112, v113
	v_cvt_pk_bf16_f32 v11, v114, v115
	v_cvt_pk_bf16_f32 v12, v116, v117
	v_cvt_pk_bf16_f32 v13, v118, v119
	ds_read_b64_tr_b16 v[116:117], v182 offset:28928
	ds_read_b64_tr_b16 v[118:119], v182 offset:30080
	v_exp_f32_e32 v120, v120
	v_exp_f32_e32 v121, v121
	v_exp_f32_e32 v122, v122
	v_exp_f32_e32 v123, v123
	v_exp_f32_e32 v124, v124
	v_exp_f32_e32 v125, v125
	v_exp_f32_e32 v126, v126
	v_exp_f32_e32 v127, v127
	v_add_f32_e32 v14, v14, v120
	v_add_f32_e32 v15, v15, v121
	v_add_f32_e32 v14, v14, v122
	v_add_f32_e32 v15, v15, v123
	v_add_f32_e32 v14, v14, v124
	v_add_f32_e32 v15, v15, v125
	v_add_f32_e32 v14, v14, v126
	v_add_f32_e32 v15, v15, v127
	v_cvt_pk_bf16_f32 v112, v120, v121
	v_cvt_pk_bf16_f32 v113, v122, v123
	v_cvt_pk_bf16_f32 v114, v124, v125
	v_cvt_pk_bf16_f32 v115, v126, v127
	ds_read_b64_tr_b16 v[120:121], v182 offset:28992
	ds_read_b64_tr_b16 v[122:123], v182 offset:30144
	s_nop 0
	v_mfma_f32_32x32x16_bf16 v[32:47], v[2:5], v[10:13], v[32:47]
	ds_read_b64_tr_b16 v[2:3], v182 offset:31232
	ds_read_b64_tr_b16 v[4:5], v182 offset:32384
	v_exp_f32_e32 v96, v96
	v_exp_f32_e32 v97, v97
	v_exp_f32_e32 v98, v98
	v_exp_f32_e32 v99, v99
	v_exp_f32_e32 v100, v100
	v_exp_f32_e32 v101, v101
	v_mfma_f32_32x32x16_bf16 v[16:31], v[6:9], v[10:13], v[16:31]
	ds_read_b64_tr_b16 v[6:7], v182 offset:31296
	ds_read_b64_tr_b16 v[8:9], v182 offset:32448
	v_exp_f32_e32 v102, v102
	v_exp_f32_e32 v103, v103
	v_add_f32_e32 v14, v14, v96
	v_add_f32_e32 v15, v15, v97
	v_add_f32_e32 v14, v14, v98
	v_add_f32_e32 v15, v15, v99
	v_add_f32_e32 v14, v14, v100
	v_add_f32_e32 v15, v15, v101
	v_add_f32_e32 v14, v14, v102
	v_add_f32_e32 v15, v15, v103
	v_cvt_pk_bf16_f32 v124, v96, v97
	v_cvt_pk_bf16_f32 v125, v98, v99
	v_cvt_pk_bf16_f32 v126, v100, v101
	v_cvt_pk_bf16_f32 v127, v102, v103
	s_waitcnt lgkmcnt(6)
	v_mfma_f32_32x32x16_bf16 v[32:47], v[116:119], v[112:115], v[32:47]
	ds_read_b64_tr_b16 v[116:117], v182 offset:33536
	ds_read_b64_tr_b16 v[118:119], v182 offset:34688
	v_exp_f32_e32 v104, v104
	v_exp_f32_e32 v105, v105
	v_exp_f32_e32 v106, v106
	v_exp_f32_e32 v107, v107
	v_exp_f32_e32 v108, v108
	v_exp_f32_e32 v109, v109
	v_exp_f32_e32 v110, v110
	v_exp_f32_e32 v111, v111
	v_add_f32_e32 v14, v14, v104
	v_add_f32_e32 v15, v15, v105
	s_waitcnt lgkmcnt(6)
	v_mfma_f32_32x32x16_bf16 v[16:31], v[120:123], v[112:115], v[16:31]
	ds_read_b64_tr_b16 v[120:121], v182 offset:33600
	ds_read_b64_tr_b16 v[122:123], v182 offset:34752
	v_add_f32_e32 v14, v14, v106
	v_add_f32_e32 v15, v15, v107
	v_add_f32_e32 v14, v14, v108
	v_add_f32_e32 v15, v15, v109
	v_add_f32_e32 v14, v14, v110
	v_add_f32_e32 v15, v15, v111
	v_cvt_pk_bf16_f32 v10, v104, v105
	v_cvt_pk_bf16_f32 v11, v106, v107
	v_cvt_pk_bf16_f32 v12, v108, v109
	v_cvt_pk_bf16_f32 v13, v110, v111
	s_waitcnt lgkmcnt(6)
	v_mfma_f32_32x32x16_bf16 v[32:47], v[2:5], v[124:127], v[32:47]
	ds_read_b64_tr_b16 v[2:3], v182 offset:35840
	ds_read_b64_tr_b16 v[4:5], v182 offset:36992
	v_exp_f32_e32 v80, v80
	v_exp_f32_e32 v81, v81
	v_exp_f32_e32 v82, v82
	v_exp_f32_e32 v83, v83
	v_exp_f32_e32 v84, v84
	v_exp_f32_e32 v85, v85
	v_exp_f32_e32 v86, v86
	v_exp_f32_e32 v87, v87
	v_add_f32_e32 v14, v14, v80
	v_add_f32_e32 v15, v15, v81
	s_waitcnt lgkmcnt(6)
	v_mfma_f32_32x32x16_bf16 v[16:31], v[6:9], v[124:127], v[16:31]
	ds_read_b64_tr_b16 v[6:7], v182 offset:35904
	ds_read_b64_tr_b16 v[8:9], v182 offset:37056
	v_add_f32_e32 v14, v14, v82
	v_add_f32_e32 v15, v15, v83
	v_add_f32_e32 v14, v14, v84
	v_add_f32_e32 v15, v15, v85
	v_add_f32_e32 v14, v14, v86
	v_add_f32_e32 v15, v15, v87
	v_cvt_pk_bf16_f32 v112, v80, v81
	v_cvt_pk_bf16_f32 v113, v82, v83
	v_cvt_pk_bf16_f32 v114, v84, v85
	v_cvt_pk_bf16_f32 v115, v86, v87
	s_waitcnt lgkmcnt(6)
; #define LAS __attribute__((address_space(3)))
; #define MFMA32(a, b, c) __builtin_amdgcn_mfma_f32_32x32x16_bf16((a), (b), (c), 0, 0, 0)
; DI s16x4 trread(LAS const char* p) { return __builtin_bit_cast(s16x4, __builtin_amdgcn_ds_read_tr16_b64_v4i16((LAS v4i16_t*)p)); }
; DI bf16x8 cat8(s16x4 lo, s16x4 hi) { return __builtin_shufflevector(lo, hi, 0, 1, 2, 3, 4, 5, 6, 7); }
; DI void mla_phase(const Args& A, LAS unsigned char* lds, int i, const int wv) {
;     ...
;             for (int kt = 0; kt < 4; ++kt)
; #pragma unroll
;                 for (int s = 0; s < 2; ++s) { const bf16x8 pb = pack8(p[kt], s);
; #pragma unroll
;                     for (int dt = 0; dt < 2; ++dt) { LAS const char* ad = (LAS const char*)vbp + (32 * kt + 16 * s + 4 * h + q_) * 144 + (32 * dt + 16 * blk) * 2 + 8 * p_;
;                         const bf16x8 va = cat8(trread(ad), trread(ad + 8 * 144)); o[dt] = MFMA32(va, pb, o[dt]); } }
;             if (j + 1 < 64) MLA_ST((j + 1) & 1);
;             __syncthreads();
;         }
	v_mfma_f32_32x32x16_bf16 v[32:47], v[116:119], v[10:13], v[32:47]
	ds_read_b64_tr_b16 v[116:117], v182 offset:38144
	ds_read_b64_tr_b16 v[118:119], v182 offset:39296
	v_exp_f32_e32 v88, v88
	v_exp_f32_e32 v89, v89
	v_exp_f32_e32 v90, v90
	v_exp_f32_e32 v91, v91
	v_exp_f32_e32 v92, v92
	v_exp_f32_e32 v93, v93
	v_exp_f32_e32 v94, v94
	v_exp_f32_e32 v95, v95
	v_add_f32_e32 v14, v14, v88
	v_add_f32_e32 v15, v15, v89
	s_waitcnt lgkmcnt(6)
	v_mfma_f32_32x32x16_bf16 v[16:31], v[120:123], v[10:13], v[16:31]
	ds_read_b64_tr_b16 v[120:121], v182 offset:38208
	ds_read_b64_tr_b16 v[122:123], v182 offset:39360
	v_add_f32_e32 v14, v14, v90
	v_add_f32_e32 v15, v15, v91
	v_add_f32_e32 v14, v14, v92
	v_add_f32_e32 v15, v15, v93
	v_add_f32_e32 v14, v14, v94
	v_add_f32_e32 v15, v15, v95
	v_cvt_pk_bf16_f32 v124, v88, v89
	v_cvt_pk_bf16_f32 v125, v90, v91
	v_cvt_pk_bf16_f32 v126, v92, v93
	v_cvt_pk_bf16_f32 v127, v94, v95
	s_waitcnt lgkmcnt(6)
	v_mfma_f32_32x32x16_bf16 v[32:47], v[2:5], v[112:115], v[32:47]
	ds_read_b64_tr_b16 v[2:3], v182 offset:40448
	ds_read_b64_tr_b16 v[4:5], v182 offset:41600
	v_exp_f32_e32 v64, v64
	v_exp_f32_e32 v65, v65
	v_exp_f32_e32 v66, v66
	v_exp_f32_e32 v67, v67
	v_exp_f32_e32 v68, v68
	v_exp_f32_e32 v69, v69
	v_exp_f32_e32 v70, v70
	v_exp_f32_e32 v71, v71
	v_add_f32_e32 v14, v14, v64
	v_add_f32_e32 v15, v15, v65
	s_waitcnt lgkmcnt(6)
	v_mfma_f32_32x32x16_bf16 v[16:31], v[6:9], v[112:115], v[16:31]
	ds_read_b64_tr_b16 v[6:7], v182 offset:40512
	ds_read_b64_tr_b16 v[8:9], v182 offset:41664
	v_add_f32_e32 v14, v14, v66
	v_add_f32_e32 v15, v15, v67
	v_add_f32_e32 v14, v14, v68
	v_add_f32_e32 v15, v15, v69
	v_add_f32_e32 v14, v14, v70
	v_add_f32_e32 v15, v15, v71
	v_cvt_pk_bf16_f32 v10, v64, v65
	v_cvt_pk_bf16_f32 v11, v66, v67
	v_cvt_pk_bf16_f32 v12, v68, v69
	v_cvt_pk_bf16_f32 v13, v70, v71
	s_waitcnt lgkmcnt(6)
	v_mfma_f32_32x32x16_bf16 v[32:47], v[116:119], v[124:127], v[32:47]
	ds_read_b64_tr_b16 v[116:117], v182 offset:42752
	ds_read_b64_tr_b16 v[118:119], v182 offset:43904
	v_exp_f32_e32 v72, v72
	v_exp_f32_e32 v73, v73
	v_exp_f32_e32 v74, v74
	v_exp_f32_e32 v75, v75
	v_exp_f32_e32 v76, v76
	v_exp_f32_e32 v77, v77
	v_exp_f32_e32 v78, v78
	v_exp_f32_e32 v79, v79
	v_add_f32_e32 v14, v14, v72
	v_add_f32_e32 v15, v15, v73
	s_waitcnt lgkmcnt(6)
	v_mfma_f32_32x32x16_bf16 v[16:31], v[120:123], v[124:127], v[16:31]
	ds_read_b64_tr_b16 v[120:121], v182 offset:42816
	ds_read_b64_tr_b16 v[122:123], v182 offset:43968
	v_add_f32_e32 v14, v14, v74
	v_add_f32_e32 v15, v15, v75
	v_add_f32_e32 v14, v14, v76
	v_add_f32_e32 v15, v15, v77
	v_add_f32_e32 v14, v14, v78
	v_add_f32_e32 v15, v15, v79
	v_cvt_pk_bf16_f32 v112, v72, v73
	v_cvt_pk_bf16_f32 v113, v74, v75
	v_cvt_pk_bf16_f32 v114, v76, v77
	v_cvt_pk_bf16_f32 v115, v78, v79
	s_nop 0
	s_waitcnt lgkmcnt(6)
	v_mfma_f32_32x32x16_bf16 v[32:47], v[2:5], v[10:13], v[32:47]
	v_add_f32_e32 v14, v14, v15
	s_waitcnt lgkmcnt(4)
	v_mfma_f32_32x32x16_bf16 v[16:31], v[6:9], v[10:13], v[16:31]
	v_add_f32_e32 v0, v0, v14
	s_waitcnt lgkmcnt(2)
	v_mfma_f32_32x32x16_bf16 v[32:47], v[116:119], v[112:115], v[32:47]
	s_waitcnt lgkmcnt(0)
	v_mfma_f32_32x32x16_bf16 v[16:31], v[120:123], v[112:115], v[16:31]
	s_cmp_eq_u32 s7, 63
	s_cbranch_scc1 .Lmla_a_nost
	s_bitcmp0_b32 s7, 0
	s_cselect_b32 s2, 0xb000, 0
	v_add3_u32 v183, s2, v251, v252
	s_waitcnt vmcnt(4)
	ds_write_b128 v183, v[128:131]
	v_add3_u32 v242, s2, v239, v172
	s_waitcnt vmcnt(3)
	ds_write_b128 v242, v[132:135]
	v_add3_u32 v183, s2, v173, v174
	s_waitcnt vmcnt(2)
	ds_write_b128 v183, v[136:139]
	v_add_u32_e32 v242, s2, v246
	v_add_u32_e32 v183, v242, v175
	v_add_u32_e32 v242, v242, v234
	s_waitcnt vmcnt(1)
	ds_write_b128 v183, v[140:143] offset:26624
	s_waitcnt vmcnt(0)
	ds_write_b128 v242, v[144:147] offset:26624
.Lmla_a_nost:
	s_add_i32 s7, s7, 1
	s_cmp_eq_u32 s7, 64
	s_waitcnt lgkmcnt(0)
	s_barrier
	s_cbranch_scc0 .LBB1_887
	s_branch .LBB1_884

; #define LAS __attribute__((address_space(3)))
; #define MFMA32(a, b, c) __builtin_amdgcn_mfma_f32_32x32x16_bf16((a), (b), (c), 0, 0, 0)
; DI s16x4 trread(LAS const char* p) { return __builtin_bit_cast(s16x4, __builtin_amdgcn_ds_read_tr16_b64_v4i16((LAS v4i16_t*)p)); }
; DI bf16x8 cat8(s16x4 lo, s16x4 hi) { return __builtin_shufflevector(lo, hi, 0, 1, 2, 3, 4, 5, 6, 7); }
; DI void mla_phase(const Args& A, LAS unsigned char* lds, int i, const int wv) {
;     ...
;             float ls = 0.f;
; #pragma unroll
;             for (int kt = 0; kt < 4; ++kt)
; #pragma unroll
;                 for (int rg = 0; rg < 16; ++rg) { p[kt][rg] = __builtin_amdgcn_exp2f(p[kt][rg]); ls += p[kt][rg]; }
;             l += ls;
; #pragma unroll
;             for (int kt = 0; kt < 4; ++kt)
; #pragma unroll
;                 for (int s = 0; s < 2; ++s) { const bf16x8 pb = pack8(p[kt], s);
; #pragma unroll
;                     for (int dt = 0; dt < 2; ++dt) { LAS const char* ad = (LAS const char*)vbp + (32 * kt + 16 * s + 4 * h + q_) * 144 + (32 * dt + 16 * blk) * 2 + 8 * p_;
;                         const bf16x8 va = cat8(trread(ad), trread(ad + 8 * 144)); o[dt] = MFMA32(va, pb, o[dt]); } }
.Lmla_b_nold:
	s_cmp_eq_u32 s7, 0
	s_cbranch_scc1 .Lmla_b_nopv
	ds_read_b64_tr_b16 v[2:3], v182 offset:26624
	ds_read_b64_tr_b16 v[4:5], v182 offset:27776
	ds_read_b64_tr_b16 v[6:7], v182 offset:26688
	ds_read_b64_tr_b16 v[8:9], v182 offset:27840
	v_exp_f32_e32 v112, v112
	v_exp_f32_e32 v113, v113
	v_exp_f32_e32 v114, v114
	v_exp_f32_e32 v115, v115
	v_exp_f32_e32 v116, v116
	v_exp_f32_e32 v117, v117
	v_exp_f32_e32 v118, v118
	v_exp_f32_e32 v119, v119
	v_add_f32_e32 v14, v112, v113
	v_add_f32_e32 v15, v114, v115
	v_add_f32_e32 v14, v14, v116
	v_add_f32_e32 v15, v15, v117
	v_add_f32_e32 v14, v14, v118
	v_add_f32_e32 v15, v15, v119
	v_cvt_pk_bf16_f32 v10, v112, v113
	v_cvt_pk_bf16_f32 v11, v114, v115
	v_cvt_pk_bf16_f32 v12, v116, v117
	v_cvt_pk_bf16_f32 v13, v118, v119
	ds_read_b64_tr_b16 v[116:117], v182 offset:28928
	ds_read_b64_tr_b16 v[118:119], v182 offset:30080
	v_exp_f32_e32 v120, v120
	v_exp_f32_e32 v121, v121
	v_exp_f32_e32 v122, v122
	v_exp_f32_e32 v123, v123
	v_exp_f32_e32 v124, v124
	v_exp_f32_e32 v125, v125
	v_exp_f32_e32 v126, v126
	v_exp_f32_e32 v127, v127
	v_add_f32_e32 v14, v14, v120
	v_add_f32_e32 v15, v15, v121
	v_add_f32_e32 v14, v14, v122
	v_add_f32_e32 v15, v15, v123
	v_add_f32_e32 v14, v14, v124
	v_add_f32_e32 v15, v15, v125
	v_add_f32_e32 v14, v14, v126
	v_add_f32_e32 v15, v15, v127
	v_cvt_pk_bf16_f32 v112, v120, v121
	v_cvt_pk_bf16_f32 v113, v122, v123
	v_cvt_pk_bf16_f32 v114, v124, v125
	v_cvt_pk_bf16_f32 v115, v126, v127
	ds_read_b64_tr_b16 v[120:121], v182 offset:28992
	ds_read_b64_tr_b16 v[122:123], v182 offset:30144
	s_nop 0
	s_waitcnt lgkmcnt(6)
	v_mfma_f32_32x32x16_bf16 v[32:47], v[2:5], v[10:13], v[32:47]
	ds_read_b64_tr_b16 v[2:3], v182 offset:31232
	ds_read_b64_tr_b16 v[4:5], v182 offset:32384
	v_exp_f32_e32 v96, v96
	v_exp_f32_e32 v97, v97
	v_exp_f32_e32 v98, v98
	v_exp_f32_e32 v99, v99
	v_exp_f32_e32 v100, v100
	v_exp_f32_e32 v101, v101
	s_waitcnt lgkmcnt(6)
	v_mfma_f32_32x32x16_bf16 v[16:31], v[6:9], v[10:13], v[16:31]
	ds_read_b64_tr_b16 v[6:7], v182 offset:31296
	ds_read_b64_tr_b16 v[8:9], v182 offset:32448
	v_exp_f32_e32 v102, v102
	v_exp_f32_e32 v103, v103
	v_add_f32_e32 v14, v14, v96
	v_add_f32_e32 v15, v15, v97
	v_add_f32_e32 v14, v14, v98
	v_add_f32_e32 v15, v15, v99
	v_add_f32_e32 v14, v14, v100
	v_add_f32_e32 v15, v15, v101
	v_add_f32_e32 v14, v14, v102
	v_add_f32_e32 v15, v15, v103
	v_cvt_pk_bf16_f32 v124, v96, v97
	v_cvt_pk_bf16_f32 v125, v98, v99
	v_cvt_pk_bf16_f32 v126, v100, v101
	v_cvt_pk_bf16_f32 v127, v102, v103
	s_waitcnt lgkmcnt(6)
	v_mfma_f32_32x32x16_bf16 v[32:47], v[116:119], v[112:115], v[32:47]
	ds_read_b64_tr_b16 v[116:117], v182 offset:33536
	ds_read_b64_tr_b16 v[118:119], v182 offset:34688
	v_exp_f32_e32 v104, v104
	v_exp_f32_e32 v105, v105
	v_exp_f32_e32 v106, v106
	v_exp_f32_e32 v107, v107
	v_exp_f32_e32 v108, v108
	v_exp_f32_e32 v109, v109
	v_exp_f32_e32 v110, v110
	v_exp_f32_e32 v111, v111
	v_add_f32_e32 v14, v14, v104
	v_add_f32_e32 v15, v15, v105
	s_waitcnt lgkmcnt(6)
	v_mfma_f32_32x32x16_bf16 v[16:31], v[120:123], v[112:115], v[16:31]
	ds_read_b64_tr_b16 v[120:121], v182 offset:33600
	ds_read_b64_tr_b16 v[122:123], v182 offset:34752
	v_add_f32_e32 v14, v14, v106
	v_add_f32_e32 v15, v15, v107
	v_add_f32_e32 v14, v14, v108
	v_add_f32_e32 v15, v15, v109
	v_add_f32_e32 v14, v14, v110
	v_add_f32_e32 v15, v15, v111
	v_cvt_pk_bf16_f32 v10, v104, v105
	v_cvt_pk_bf16_f32 v11, v106, v107
	v_cvt_pk_bf16_f32 v12, v108, v109
	v_cvt_pk_bf16_f32 v13, v110, v111
	s_waitcnt lgkmcnt(6)
	v_mfma_f32_32x32x16_bf16 v[32:47], v[2:5], v[124:127], v[32:47]
	ds_read_b64_tr_b16 v[2:3], v182 offset:35840
	ds_read_b64_tr_b16 v[4:5], v182 offset:36992
	v_exp_f32_e32 v80, v80
	v_exp_f32_e32 v81, v81
	v_exp_f32_e32 v82, v82
	v_exp_f32_e32 v83, v83
	v_exp_f32_e32 v84, v84
	v_exp_f32_e32 v85, v85
	v_exp_f32_e32 v86, v86
	v_exp_f32_e32 v87, v87
	v_add_f32_e32 v14, v14, v80
	v_add_f32_e32 v15, v15, v81
	s_waitcnt lgkmcnt(6)
	v_mfma_f32_32x32x16_bf16 v[16:31], v[6:9], v[124:127], v[16:31]
	ds_read_b64_tr_b16 v[6:7], v182 offset:35904
	ds_read_b64_tr_b16 v[8:9], v182 offset:37056
	v_add_f32_e32 v14, v14, v82
	v_add_f32_e32 v15, v15, v83
	v_add_f32_e32 v14, v14, v84
	v_add_f32_e32 v15, v15, v85
	v_add_f32_e32 v14, v14, v86
	v_add_f32_e32 v15, v15, v87
	v_cvt_pk_bf16_f32 v112, v80, v81
	v_cvt_pk_bf16_f32 v113, v82, v83
	v_cvt_pk_bf16_f32 v114, v84, v85
	v_cvt_pk_bf16_f32 v115, v86, v87
	s_waitcnt lgkmcnt(6)
	v_mfma_f32_32x32x16_bf16 v[32:47], v[116:119], v[10:13], v[32:47]
	ds_read_b64_tr_b16 v[116:117], v182 offset:38144
	ds_read_b64_tr_b16 v[118:119], v182 offset:39296
	v_exp_f32_e32 v88, v88
	v_exp_f32_e32 v89, v89
	v_exp_f32_e32 v90, v90
	v_exp_f32_e32 v91, v91
	v_exp_f32_e32 v92, v92
	v_exp_f32_e32 v93, v93
	v_exp_f32_e32 v94, v94
	v_exp_f32_e32 v95, v95
	v_add_f32_e32 v14, v14, v88
	v_add_f32_e32 v15, v15, v89
	s_waitcnt lgkmcnt(6)
	v_mfma_f32_32x32x16_bf16 v[16:31], v[120:123], v[10:13], v[16:31]
	ds_read_b64_tr_b16 v[120:121], v182 offset:38208
	ds_read_b64_tr_b16 v[122:123], v182 offset:39360
	v_add_f32_e32 v14, v14, v90
	v_add_f32_e32 v15, v15, v91
	v_add_f32_e32 v14, v14, v92
	v_add_f32_e32 v15, v15, v93
	v_add_f32_e32 v14, v14, v94
	v_add_f32_e32 v15, v15, v95
	v_cvt_pk_bf16_f32 v124, v88, v89
	v_cvt_pk_bf16_f32 v125, v90, v91
	v_cvt_pk_bf16_f32 v126, v92, v93
	v_cvt_pk_bf16_f32 v127, v94, v95
	s_waitcnt lgkmcnt(6)
	v_mfma_f32_32x32x16_bf16 v[32:47], v[2:5], v[112:115], v[32:47]
	ds_read_b64_tr_b16 v[2:3], v182 offset:40448
	ds_read_b64_tr_b16 v[4:5], v182 offset:41600
	v_exp_f32_e32 v64, v64
	v_exp_f32_e32 v65, v65
	v_exp_f32_e32 v66, v66
	v_exp_f32_e32 v67, v67
	v_exp_f32_e32 v68, v68
	v_exp_f32_e32 v69, v69
	v_exp_f32_e32 v70, v70
	v_exp_f32_e32 v71, v71
	v_add_f32_e32 v14, v14, v64
	v_add_f32_e32 v15, v15, v65
	s_waitcnt lgkmcnt(6)
; #define LAS __attribute__((address_space(3)))
; DI float shx(float v, int mask) { const int l = lane_id(); return __int_as_float(__builtin_amdgcn_ds_bpermute((l ^ mask) << 2, __float_as_int(v))); }
; #define MFMA32(a, b, c) __builtin_amdgcn_mfma_f32_32x32x16_bf16((a), (b), (c), 0, 0, 0)
; DI void mla_phase(const Args& A, LAS unsigned char* lds, int i, const int wv) {
;     ...
;         for (int j = 0; j < 64; ++j) {
;             LAS const unsigned char* kb_ = lds + (j & 1) * TB; LAS const unsigned char* vbp = kb_ + KB2;
;             if (j + 1 < 64) MLA_LD(j + 1);
;             f32x16 p[4];
; #pragma unroll
;             for (int kt = 0; kt < 4; ++kt) p[kt] = negm;
; #pragma unroll
;             for (int s = 0; s < 6; ++s)
; #pragma unroll
;                 for (int kt = 0; kt < 4; ++kt) { const bf16x8 ka = *(LAS const bf16x8*)(kb_ + (32 * kt + r32) * 208 + 32 * s + 16 * h); p[kt] = MFMA32(ka, qf[s], p[kt]); }
;             float mx = fmaxf(fmaxf(p[0][0], p[1][0]), fmaxf(p[2][0], p[3][0]));
; #pragma unroll
;             for (int rg = 1; rg < 16; ++rg) mx = fmaxf(mx, fmaxf(fmaxf(p[0][rg], p[1][rg]), fmaxf(p[2][rg], p[3][rg])));
;             mx = fmaxf(mx, shx(mx, 32));
;             if (__any(mx > 8.0f)) {
	v_mfma_f32_32x32x16_bf16 v[16:31], v[6:9], v[112:115], v[16:31]
	ds_read_b64_tr_b16 v[6:7], v182 offset:40512
	ds_read_b64_tr_b16 v[8:9], v182 offset:41664
	v_add_f32_e32 v14, v14, v66
	v_add_f32_e32 v15, v15, v67
	v_add_f32_e32 v14, v14, v68
	v_add_f32_e32 v15, v15, v69
	v_add_f32_e32 v14, v14, v70
	v_add_f32_e32 v15, v15, v71
	v_cvt_pk_bf16_f32 v10, v64, v65
	v_cvt_pk_bf16_f32 v11, v66, v67
	v_cvt_pk_bf16_f32 v12, v68, v69
	v_cvt_pk_bf16_f32 v13, v70, v71
	s_waitcnt lgkmcnt(6)
	v_mfma_f32_32x32x16_bf16 v[32:47], v[116:119], v[124:127], v[32:47]
	ds_read_b64_tr_b16 v[116:117], v182 offset:42752
	ds_read_b64_tr_b16 v[118:119], v182 offset:43904
	v_exp_f32_e32 v72, v72
	v_exp_f32_e32 v73, v73
	v_exp_f32_e32 v74, v74
	v_exp_f32_e32 v75, v75
	v_exp_f32_e32 v76, v76
	v_exp_f32_e32 v77, v77
	v_exp_f32_e32 v78, v78
	v_exp_f32_e32 v79, v79
	v_add_f32_e32 v14, v14, v72
	v_add_f32_e32 v15, v15, v73
	s_waitcnt lgkmcnt(6)
	v_mfma_f32_32x32x16_bf16 v[16:31], v[120:123], v[124:127], v[16:31]
	ds_read_b64_tr_b16 v[120:121], v182 offset:42816
	ds_read_b64_tr_b16 v[122:123], v182 offset:43968
	v_add_f32_e32 v14, v14, v74
	v_add_f32_e32 v15, v15, v75
	v_add_f32_e32 v14, v14, v76
	v_add_f32_e32 v15, v15, v77
	v_add_f32_e32 v14, v14, v78
	v_add_f32_e32 v15, v15, v79
	v_cvt_pk_bf16_f32 v112, v72, v73
	v_cvt_pk_bf16_f32 v113, v74, v75
	v_cvt_pk_bf16_f32 v114, v76, v77
	v_cvt_pk_bf16_f32 v115, v78, v79
	s_nop 0
	s_waitcnt lgkmcnt(6)
	v_mfma_f32_32x32x16_bf16 v[32:47], v[2:5], v[10:13], v[32:47]
	v_add_f32_e32 v14, v14, v15
	s_waitcnt lgkmcnt(4)
	v_mfma_f32_32x32x16_bf16 v[16:31], v[6:9], v[10:13], v[16:31]
	v_add_f32_e32 v0, v0, v14
	s_waitcnt lgkmcnt(2)
	v_mfma_f32_32x32x16_bf16 v[32:47], v[116:119], v[112:115], v[32:47]
	s_waitcnt lgkmcnt(0)
	v_mfma_f32_32x32x16_bf16 v[16:31], v[120:123], v[112:115], v[16:31]
.Lmla_b_nopv:
	s_barrier
	s_bitcmp1_b32 s7, 0
	s_cselect_b32 s4, 0xb000, 0
	v_add3_u32 v183, s4, v248, v235
	ds_read_b128 v[2:5], v183 offset:0
	ds_read_b128 v[6:9], v183 offset:32
	ds_read_b128 v[10:13], v183 offset:64
	ds_read_b128 v[64:67], v183 offset:96
	ds_read_b128 v[68:71], v183 offset:128
	ds_read_b128 v[72:75], v183 offset:160
	ds_read_b128 v[76:79], v183 offset:6656
	s_waitcnt lgkmcnt(6)
	v_mfma_f32_32x32x16_bf16 v[112:127], v[2:5], v[148:151], v[48:63]
	ds_read_b128 v[2:5], v183 offset:6688
	v_add_u32_e32 v182, s4, v249
	s_waitcnt lgkmcnt(6)
	v_mfma_f32_32x32x16_bf16 v[112:127], v[6:9], v[152:155], v[112:127]
	ds_read_b128 v[6:9], v183 offset:6720
	v_add3_u32 v182, v182, v250, v238
	s_waitcnt lgkmcnt(6)
	v_mfma_f32_32x32x16_bf16 v[112:127], v[10:13], v[156:159], v[112:127]
	ds_read_b128 v[10:13], v183 offset:6752
	v_lshl_add_u64 v[222:223], v[222:223], 0, s[52:53]
	v_lshl_add_u64 v[224:225], v[224:225], 0, s[52:53]
	s_waitcnt lgkmcnt(6)
	v_mfma_f32_32x32x16_bf16 v[112:127], v[64:67], v[160:163], v[112:127]
	ds_read_b128 v[64:67], v183 offset:6784
	v_lshl_add_u64 v[226:227], v[226:227], 0, s[54:55]
	v_lshl_add_u64 v[228:229], v[228:229], 0, s[54:55]
	s_waitcnt lgkmcnt(6)
	v_mfma_f32_32x32x16_bf16 v[112:127], v[68:71], v[164:167], v[112:127]
	ds_read_b128 v[68:71], v183 offset:6816
	v_lshl_add_u64 v[230:231], v[230:231], 0, s[54:55]
	s_waitcnt lgkmcnt(6)
	v_mfma_f32_32x32x16_bf16 v[112:127], v[72:75], v[168:171], v[112:127]
	ds_read_b128 v[72:75], v183 offset:13312
	v_mbcnt_lo_u32_b32 v243, -1, 0
	v_mbcnt_hi_u32_b32 v243, -1, v243
	s_waitcnt lgkmcnt(6)
	v_mfma_f32_32x32x16_bf16 v[96:111], v[76:79], v[148:151], v[48:63]
	ds_read_b128 v[76:79], v183 offset:13344
	v_lshlrev_b32_e32 v243, 2, v243
	s_waitcnt lgkmcnt(6)
	v_mfma_f32_32x32x16_bf16 v[96:111], v[2:5], v[152:155], v[96:111]
	ds_read_b128 v[2:5], v183 offset:13376
	v_xor_b32_e32 v243, 0x80, v243
	s_waitcnt lgkmcnt(6)
	v_mfma_f32_32x32x16_bf16 v[96:111], v[6:9], v[156:159], v[96:111]
	ds_read_b128 v[6:9], v183 offset:13408
	s_waitcnt lgkmcnt(6)
	v_mfma_f32_32x32x16_bf16 v[96:111], v[10:13], v[160:163], v[96:111]
	ds_read_b128 v[10:13], v183 offset:13440
	v_max3_f32 v14, v112, v113, v114
	v_max3_f32 v14, v14, v115, v116
	v_max3_f32 v14, v14, v117, v118
	s_waitcnt lgkmcnt(6)
	v_mfma_f32_32x32x16_bf16 v[96:111], v[64:67], v[164:167], v[96:111]
	ds_read_b128 v[64:67], v183 offset:13472
	v_max3_f32 v14, v14, v119, v120
	v_max3_f32 v14, v14, v121, v122
	v_max3_f32 v14, v14, v123, v124
	s_waitcnt lgkmcnt(6)
	v_mfma_f32_32x32x16_bf16 v[96:111], v[68:71], v[168:171], v[96:111]
	v_max3_f32 v14, v14, v125, v126
	v_max_f32_e32 v14, v14, v127
	s_waitcnt lgkmcnt(5)
	v_mfma_f32_32x32x16_bf16 v[80:95], v[72:75], v[148:151], v[48:63]
	s_waitcnt lgkmcnt(4)
	v_mfma_f32_32x32x16_bf16 v[80:95], v[76:79], v[152:155], v[80:95]
	s_waitcnt lgkmcnt(3)
	v_mfma_f32_32x32x16_bf16 v[80:95], v[2:5], v[156:159], v[80:95]
	ds_read_b128 v[2:5], v183 offset:19968
	s_waitcnt lgkmcnt(3)
	v_mfma_f32_32x32x16_bf16 v[80:95], v[6:9], v[160:163], v[80:95]
	ds_read_b128 v[6:9], v183 offset:20000
	v_max3_f32 v14, v14, v96, v97
	v_max3_f32 v14, v14, v98, v99
	v_max3_f32 v14, v14, v100, v101
	s_waitcnt lgkmcnt(3)
	v_mfma_f32_32x32x16_bf16 v[80:95], v[10:13], v[164:167], v[80:95]
	ds_read_b128 v[10:13], v183 offset:20032
	v_max3_f32 v14, v14, v102, v103
	v_max3_f32 v14, v14, v104, v105
	v_max3_f32 v14, v14, v106, v107
	s_waitcnt lgkmcnt(3)
	v_mfma_f32_32x32x16_bf16 v[80:95], v[64:67], v[168:171], v[80:95]
	v_max3_f32 v14, v14, v108, v109
	v_max3_f32 v14, v14, v110, v111
	s_waitcnt lgkmcnt(2)
	v_mfma_f32_32x32x16_bf16 v[64:79], v[2:5], v[148:151], v[48:63]
	ds_read_b128 v[2:5], v183 offset:20064
	s_waitcnt lgkmcnt(2)
	v_mfma_f32_32x32x16_bf16 v[64:79], v[6:9], v[152:155], v[64:79]
	ds_read_b128 v[6:9], v183 offset:20096
	s_waitcnt lgkmcnt(2)
	v_mfma_f32_32x32x16_bf16 v[64:79], v[10:13], v[156:159], v[64:79]
	ds_read_b128 v[10:13], v183 offset:20128
	s_waitcnt lgkmcnt(2)
	v_mfma_f32_32x32x16_bf16 v[64:79], v[2:5], v[160:163], v[64:79]
	v_max3_f32 v14, v14, v80, v81
	v_max3_f32 v14, v14, v82, v83
	v_max3_f32 v14, v14, v84, v85
	s_waitcnt lgkmcnt(1)
	v_mfma_f32_32x32x16_bf16 v[64:79], v[6:9], v[164:167], v[64:79]
	v_max3_f32 v14, v14, v86, v87
	v_max3_f32 v14, v14, v88, v89
	v_max3_f32 v14, v14, v90, v91
	s_waitcnt lgkmcnt(0)
	v_mfma_f32_32x32x16_bf16 v[64:79], v[10:13], v[168:171], v[64:79]
	v_max3_f32 v14, v14, v92, v93
	v_max3_f32 v14, v14, v94, v95
	s_nop 9
	v_max3_f32 v14, v14, v64, v65
	v_max3_f32 v14, v14, v66, v67
	v_max3_f32 v14, v14, v68, v69
	v_max3_f32 v14, v14, v70, v71
	v_max3_f32 v14, v14, v72, v73
	v_max3_f32 v14, v14, v74, v75
	v_max3_f32 v14, v14, v76, v77
	v_max3_f32 v14, v14, v78, v79
	ds_bpermute_b32 v15, v243, v14
	s_waitcnt lgkmcnt(0)
	v_max_f32_e32 v14, v14, v15
	s_mov_b32 s6, 0x41000000
	v_cmp_lt_f32_e32 vcc, s6, v14
	s_cbranch_vccz .Lmla_b_norescale
; DI void mla_phase(const Args& A, LAS unsigned char* lds, int i, const int wv) {
;     ...
;             if (__any(mx > 8.0f)) {
;                 const float dl = fmaxf(mx, 0.f), alpha = __builtin_amdgcn_exp2f(-dl); mrow += dl; l *= alpha;
; #pragma unroll
;                 for (int rg = 0; rg < 16; ++rg) { p[0][rg] -= dl; p[1][rg] -= dl; p[2][rg] -= dl; p[3][rg] -= dl; o[0][rg] *= alpha; o[1][rg] *= alpha; negm[rg] = -mrow; }
;             }
;     ...
;             if (j + 1 < 64) MLA_ST((j + 1) & 1);
	v_max_f32_e32 v14, 0, v14
	v_exp_f32_e64 v242, -v14
	v_add_f32_e32 v181, v181, v14
	v_xor_b32_e32 v48, 0x80000000, v181
	v_pk_add_f32 v[112:113], v[112:113], v[14:15] op_sel_hi:[1,0] neg_lo:[0,1] neg_hi:[0,1]
	v_pk_add_f32 v[96:97], v[96:97], v[14:15] op_sel_hi:[1,0] neg_lo:[0,1] neg_hi:[0,1]
	v_pk_add_f32 v[80:81], v[80:81], v[14:15] op_sel_hi:[1,0] neg_lo:[0,1] neg_hi:[0,1]
	v_pk_add_f32 v[64:65], v[64:65], v[14:15] op_sel_hi:[1,0] neg_lo:[0,1] neg_hi:[0,1]
	v_pk_add_f32 v[114:115], v[114:115], v[14:15] op_sel_hi:[1,0] neg_lo:[0,1] neg_hi:[0,1]
	v_pk_add_f32 v[98:99], v[98:99], v[14:15] op_sel_hi:[1,0] neg_lo:[0,1] neg_hi:[0,1]
	v_pk_add_f32 v[82:83], v[82:83], v[14:15] op_sel_hi:[1,0] neg_lo:[0,1] neg_hi:[0,1]
	v_pk_add_f32 v[66:67], v[66:67], v[14:15] op_sel_hi:[1,0] neg_lo:[0,1] neg_hi:[0,1]
	v_pk_add_f32 v[116:117], v[116:117], v[14:15] op_sel_hi:[1,0] neg_lo:[0,1] neg_hi:[0,1]
	v_pk_add_f32 v[100:101], v[100:101], v[14:15] op_sel_hi:[1,0] neg_lo:[0,1] neg_hi:[0,1]
	v_pk_add_f32 v[84:85], v[84:85], v[14:15] op_sel_hi:[1,0] neg_lo:[0,1] neg_hi:[0,1]
	v_pk_add_f32 v[68:69], v[68:69], v[14:15] op_sel_hi:[1,0] neg_lo:[0,1] neg_hi:[0,1]
	v_pk_add_f32 v[118:119], v[118:119], v[14:15] op_sel_hi:[1,0] neg_lo:[0,1] neg_hi:[0,1]
	v_pk_add_f32 v[102:103], v[102:103], v[14:15] op_sel_hi:[1,0] neg_lo:[0,1] neg_hi:[0,1]
	v_pk_add_f32 v[86:87], v[86:87], v[14:15] op_sel_hi:[1,0] neg_lo:[0,1] neg_hi:[0,1]
	v_pk_add_f32 v[70:71], v[70:71], v[14:15] op_sel_hi:[1,0] neg_lo:[0,1] neg_hi:[0,1]
	v_pk_add_f32 v[120:121], v[120:121], v[14:15] op_sel_hi:[1,0] neg_lo:[0,1] neg_hi:[0,1]
	v_pk_add_f32 v[104:105], v[104:105], v[14:15] op_sel_hi:[1,0] neg_lo:[0,1] neg_hi:[0,1]
	v_pk_add_f32 v[88:89], v[88:89], v[14:15] op_sel_hi:[1,0] neg_lo:[0,1] neg_hi:[0,1]
	v_pk_add_f32 v[72:73], v[72:73], v[14:15] op_sel_hi:[1,0] neg_lo:[0,1] neg_hi:[0,1]
	v_pk_add_f32 v[122:123], v[122:123], v[14:15] op_sel_hi:[1,0] neg_lo:[0,1] neg_hi:[0,1]
	v_pk_add_f32 v[106:107], v[106:107], v[14:15] op_sel_hi:[1,0] neg_lo:[0,1] neg_hi:[0,1]
	v_pk_add_f32 v[90:91], v[90:91], v[14:15] op_sel_hi:[1,0] neg_lo:[0,1] neg_hi:[0,1]
	v_pk_add_f32 v[74:75], v[74:75], v[14:15] op_sel_hi:[1,0] neg_lo:[0,1] neg_hi:[0,1]
	v_pk_add_f32 v[124:125], v[124:125], v[14:15] op_sel_hi:[1,0] neg_lo:[0,1] neg_hi:[0,1]
	v_pk_add_f32 v[108:109], v[108:109], v[14:15] op_sel_hi:[1,0] neg_lo:[0,1] neg_hi:[0,1]
	v_pk_add_f32 v[92:93], v[92:93], v[14:15] op_sel_hi:[1,0] neg_lo:[0,1] neg_hi:[0,1]
	v_pk_add_f32 v[76:77], v[76:77], v[14:15] op_sel_hi:[1,0] neg_lo:[0,1] neg_hi:[0,1]
	v_pk_add_f32 v[126:127], v[126:127], v[14:15] op_sel_hi:[1,0] neg_lo:[0,1] neg_hi:[0,1]
	v_pk_add_f32 v[110:111], v[110:111], v[14:15] op_sel_hi:[1,0] neg_lo:[0,1] neg_hi:[0,1]
	v_pk_add_f32 v[94:95], v[94:95], v[14:15] op_sel_hi:[1,0] neg_lo:[0,1] neg_hi:[0,1]
	v_pk_add_f32 v[78:79], v[78:79], v[14:15] op_sel_hi:[1,0] neg_lo:[0,1] neg_hi:[0,1]
	v_pk_mul_f32 v[46:47], v[46:47], v[242:243] op_sel_hi:[1,0]
	v_pk_mul_f32 v[44:45], v[44:45], v[242:243] op_sel_hi:[1,0]
	v_pk_mul_f32 v[42:43], v[42:43], v[242:243] op_sel_hi:[1,0]
	v_pk_mul_f32 v[40:41], v[40:41], v[242:243] op_sel_hi:[1,0]
	v_pk_mul_f32 v[38:39], v[38:39], v[242:243] op_sel_hi:[1,0]
	v_pk_mul_f32 v[36:37], v[36:37], v[242:243] op_sel_hi:[1,0]
	v_pk_mul_f32 v[34:35], v[34:35], v[242:243] op_sel_hi:[1,0]
	v_pk_mul_f32 v[32:33], v[32:33], v[242:243] op_sel_hi:[1,0]
	v_pk_mul_f32 v[30:31], v[30:31], v[242:243] op_sel_hi:[1,0]
	v_pk_mul_f32 v[28:29], v[28:29], v[242:243] op_sel_hi:[1,0]
	v_pk_mul_f32 v[26:27], v[26:27], v[242:243] op_sel_hi:[1,0]
	v_pk_mul_f32 v[24:25], v[24:25], v[242:243] op_sel_hi:[1,0]
	v_pk_mul_f32 v[22:23], v[22:23], v[242:243] op_sel_hi:[1,0]
	v_pk_mul_f32 v[20:21], v[20:21], v[242:243] op_sel_hi:[1,0]
	v_pk_mul_f32 v[18:19], v[18:19], v[242:243] op_sel_hi:[1,0]
	v_pk_mul_f32 v[16:17], v[16:17], v[242:243] op_sel_hi:[1,0]
	v_mul_f32_e32 v0, v0, v242
	v_mov_b32_e32 v49, v48
	v_mov_b32_e32 v50, v48
	v_mov_b32_e32 v51, v48
	v_mov_b32_e32 v52, v48
	v_mov_b32_e32 v53, v48
	v_mov_b32_e32 v54, v48
	v_mov_b32_e32 v55, v48
	v_mov_b32_e32 v56, v48
	v_mov_b32_e32 v57, v48
	v_mov_b32_e32 v58, v48
	v_mov_b32_e32 v59, v48
	v_mov_b32_e32 v60, v48
	v_mov_b32_e32 v61, v48
	v_mov_b32_e32 v62, v48
	v_mov_b32_e32 v63, v48
.Lmla_b_norescale:
	s_cmp_eq_u32 s7, 63
	s_cbranch_scc1 .Lmla_b_nost
	s_bitcmp0_b32 s7, 0
	s_cselect_b32 s2, 0xb000, 0
	v_add3_u32 v183, s2, v251, v252
	s_waitcnt vmcnt(4)
	ds_write_b128 v183, v[128:131]
	v_add3_u32 v242, s2, v239, v172
	s_waitcnt vmcnt(3)
	ds_write_b128 v242, v[132:135]
	v_add3_u32 v183, s2, v173, v174
	s_waitcnt vmcnt(2)
	ds_write_b128 v183, v[136:139]
	v_add_u32_e32 v242, s2, v246
	v_add_u32_e32 v183, v242, v175
	v_add_u32_e32 v242, v242, v234
	s_waitcnt vmcnt(1)
	ds_write_b128 v183, v[140:143] offset:26624
	s_waitcnt vmcnt(0)
	ds_write_b128 v242, v[144:147] offset:26624
; #define LAS __attribute__((address_space(3)))
; #define MFMA32(a, b, c) __builtin_amdgcn_mfma_f32_32x32x16_bf16((a), (b), (c), 0, 0, 0)
; DI s16x4 trread(LAS const char* p) { return __builtin_bit_cast(s16x4, __builtin_amdgcn_ds_read_tr16_b64_v4i16((LAS v4i16_t*)p)); }
; DI bf16x8 cat8(s16x4 lo, s16x4 hi) { return __builtin_shufflevector(lo, hi, 0, 1, 2, 3, 4, 5, 6, 7); }
; DI void mla_phase(const Args& A, LAS unsigned char* lds, int i, const int wv) {
;     ...
;             float ls = 0.f;
; #pragma unroll
;             for (int kt = 0; kt < 4; ++kt)
; #pragma unroll
;                 for (int rg = 0; rg < 16; ++rg) { p[kt][rg] = __builtin_amdgcn_exp2f(p[kt][rg]); ls += p[kt][rg]; }
;             l += ls;
; #pragma unroll
;             for (int kt = 0; kt < 4; ++kt)
; #pragma unroll
;                 for (int s = 0; s < 2; ++s) { const bf16x8 pb = pack8(p[kt], s);
; #pragma unroll
;                     for (int dt = 0; dt < 2; ++dt) { LAS const char* ad = (LAS const char*)vbp + (32 * kt + 16 * s + 4 * h + q_) * 144 + (32 * dt + 16 * blk) * 2 + 8 * p_;
;                         const bf16x8 va = cat8(trread(ad), trread(ad + 8 * 144)); o[dt] = MFMA32(va, pb, o[dt]); } }
;             if (j + 1 < 64) MLA_ST((j + 1) & 1);
;             __syncthreads();
;         }
.Lmla_b_nost:
	s_add_i32 s7, s7, 1
	s_cmp_eq_u32 s7, 64
	s_waitcnt lgkmcnt(0)
	s_barrier
	s_cbranch_scc0 .Lmla_late_top
	ds_read_b64_tr_b16 v[2:3], v182 offset:26624
	ds_read_b64_tr_b16 v[4:5], v182 offset:27776
	ds_read_b64_tr_b16 v[6:7], v182 offset:26688
	ds_read_b64_tr_b16 v[8:9], v182 offset:27840
	v_exp_f32_e32 v112, v112
	v_exp_f32_e32 v113, v113
	v_exp_f32_e32 v114, v114
	v_exp_f32_e32 v115, v115
	v_exp_f32_e32 v116, v116
	v_exp_f32_e32 v117, v117
	v_exp_f32_e32 v118, v118
	v_exp_f32_e32 v119, v119
	v_add_f32_e32 v14, v112, v113
	v_add_f32_e32 v15, v114, v115
	v_add_f32_e32 v14, v14, v116
	v_add_f32_e32 v15, v15, v117
	v_add_f32_e32 v14, v14, v118
	v_add_f32_e32 v15, v15, v119
	v_cvt_pk_bf16_f32 v10, v112, v113
	v_cvt_pk_bf16_f32 v11, v114, v115
	v_cvt_pk_bf16_f32 v12, v116, v117
	v_cvt_pk_bf16_f32 v13, v118, v119
	ds_read_b64_tr_b16 v[116:117], v182 offset:28928
	ds_read_b64_tr_b16 v[118:119], v182 offset:30080
	v_exp_f32_e32 v120, v120
	v_exp_f32_e32 v121, v121
	v_exp_f32_e32 v122, v122
	v_exp_f32_e32 v123, v123
	v_exp_f32_e32 v124, v124
	v_exp_f32_e32 v125, v125
	v_exp_f32_e32 v126, v126
	v_exp_f32_e32 v127, v127
	v_add_f32_e32 v14, v14, v120
	v_add_f32_e32 v15, v15, v121
	v_add_f32_e32 v14, v14, v122
	v_add_f32_e32 v15, v15, v123
	v_add_f32_e32 v14, v14, v124
	v_add_f32_e32 v15, v15, v125
	v_add_f32_e32 v14, v14, v126
	v_add_f32_e32 v15, v15, v127
	v_cvt_pk_bf16_f32 v112, v120, v121
	v_cvt_pk_bf16_f32 v113, v122, v123
	v_cvt_pk_bf16_f32 v114, v124, v125
	v_cvt_pk_bf16_f32 v115, v126, v127
	ds_read_b64_tr_b16 v[120:121], v182 offset:28992
	ds_read_b64_tr_b16 v[122:123], v182 offset:30144
	s_nop 0
	s_waitcnt lgkmcnt(6)
	v_mfma_f32_32x32x16_bf16 v[32:47], v[2:5], v[10:13], v[32:47]
	ds_read_b64_tr_b16 v[2:3], v182 offset:31232
	ds_read_b64_tr_b16 v[4:5], v182 offset:32384
	v_exp_f32_e32 v96, v96
	v_exp_f32_e32 v97, v97
	v_exp_f32_e32 v98, v98
	v_exp_f32_e32 v99, v99
	v_exp_f32_e32 v100, v100
	v_exp_f32_e32 v101, v101
	s_waitcnt lgkmcnt(6)
	v_mfma_f32_32x32x16_bf16 v[16:31], v[6:9], v[10:13], v[16:31]
	ds_read_b64_tr_b16 v[6:7], v182 offset:31296
	ds_read_b64_tr_b16 v[8:9], v182 offset:32448
	v_exp_f32_e32 v102, v102
	v_exp_f32_e32 v103, v103
	v_add_f32_e32 v14, v14, v96
	v_add_f32_e32 v15, v15, v97
	v_add_f32_e32 v14, v14, v98
	v_add_f32_e32 v15, v15, v99
	v_add_f32_e32 v14, v14, v100
	v_add_f32_e32 v15, v15, v101
	v_add_f32_e32 v14, v14, v102
	v_add_f32_e32 v15, v15, v103
	v_cvt_pk_bf16_f32 v124, v96, v97
	v_cvt_pk_bf16_f32 v125, v98, v99
	v_cvt_pk_bf16_f32 v126, v100, v101
	v_cvt_pk_bf16_f32 v127, v102, v103
	s_waitcnt lgkmcnt(6)
	v_mfma_f32_32x32x16_bf16 v[32:47], v[116:119], v[112:115], v[32:47]
	ds_read_b64_tr_b16 v[116:117], v182 offset:33536
	ds_read_b64_tr_b16 v[118:119], v182 offset:34688
	v_exp_f32_e32 v104, v104
	v_exp_f32_e32 v105, v105
	v_exp_f32_e32 v106, v106
	v_exp_f32_e32 v107, v107
	v_exp_f32_e32 v108, v108
	v_exp_f32_e32 v109, v109
	v_exp_f32_e32 v110, v110
	v_exp_f32_e32 v111, v111
	v_add_f32_e32 v14, v14, v104
	v_add_f32_e32 v15, v15, v105
	s_waitcnt lgkmcnt(6)
	v_mfma_f32_32x32x16_bf16 v[16:31], v[120:123], v[112:115], v[16:31]
	ds_read_b64_tr_b16 v[120:121], v182 offset:33600
	ds_read_b64_tr_b16 v[122:123], v182 offset:34752
	v_add_f32_e32 v14, v14, v106
	v_add_f32_e32 v15, v15, v107
	v_add_f32_e32 v14, v14, v108
	v_add_f32_e32 v15, v15, v109
	v_add_f32_e32 v14, v14, v110
	v_add_f32_e32 v15, v15, v111
	v_cvt_pk_bf16_f32 v10, v104, v105
	v_cvt_pk_bf16_f32 v11, v106, v107
	v_cvt_pk_bf16_f32 v12, v108, v109
	v_cvt_pk_bf16_f32 v13, v110, v111
	s_waitcnt lgkmcnt(6)
	v_mfma_f32_32x32x16_bf16 v[32:47], v[2:5], v[124:127], v[32:47]
	ds_read_b64_tr_b16 v[2:3], v182 offset:35840
	ds_read_b64_tr_b16 v[4:5], v182 offset:36992
	v_exp_f32_e32 v80, v80
	v_exp_f32_e32 v81, v81
	v_exp_f32_e32 v82, v82
	v_exp_f32_e32 v83, v83
	v_exp_f32_e32 v84, v84
	v_exp_f32_e32 v85, v85
	v_exp_f32_e32 v86, v86
	v_exp_f32_e32 v87, v87
	v_add_f32_e32 v14, v14, v80
	v_add_f32_e32 v15, v15, v81
	s_waitcnt lgkmcnt(6)
; #define LAS __attribute__((address_space(3)))
; DI float shx(float v, int mask) { const int l = lane_id(); return __int_as_float(__builtin_amdgcn_ds_bpermute((l ^ mask) << 2, __float_as_int(v))); }
; #define MFMA32(a, b, c) __builtin_amdgcn_mfma_f32_32x32x16_bf16((a), (b), (c), 0, 0, 0)
; DI s16x4 trread(LAS const char* p) { return __builtin_bit_cast(s16x4, __builtin_amdgcn_ds_read_tr16_b64_v4i16((LAS v4i16_t*)p)); }
; DI bf16x8 cat8(s16x4 lo, s16x4 hi) { return __builtin_shufflevector(lo, hi, 0, 1, 2, 3, 4, 5, 6, 7); }
; DI void mla_phase(const Args& A, LAS unsigned char* lds, int i, const int wv) {
;     ...
;             float ls = 0.f;
; #pragma unroll
;             for (int kt = 0; kt < 4; ++kt)
; #pragma unroll
;                 for (int rg = 0; rg < 16; ++rg) { p[kt][rg] = __builtin_amdgcn_exp2f(p[kt][rg]); ls += p[kt][rg]; }
;             l += ls;
; #pragma unroll
;             for (int kt = 0; kt < 4; ++kt)
; #pragma unroll
;                 for (int s = 0; s < 2; ++s) { const bf16x8 pb = pack8(p[kt], s);
; #pragma unroll
;                     for (int dt = 0; dt < 2; ++dt) { LAS const char* ad = (LAS const char*)vbp + (32 * kt + 16 * s + 4 * h + q_) * 144 + (32 * dt + 16 * blk) * 2 + 8 * p_;
;                         const bf16x8 va = cat8(trread(ad), trread(ad + 8 * 144)); o[dt] = MFMA32(va, pb, o[dt]); } }
;             if (j + 1 < 64) MLA_ST((j + 1) & 1);
;             __syncthreads();
;         }
;     ...
;         l += shx(l, 32); const float inv = 1.0f / l;
	v_mfma_f32_32x32x16_bf16 v[16:31], v[6:9], v[124:127], v[16:31]
	ds_read_b64_tr_b16 v[6:7], v182 offset:35904
	ds_read_b64_tr_b16 v[8:9], v182 offset:37056
	v_add_f32_e32 v14, v14, v82
	v_add_f32_e32 v15, v15, v83
	v_add_f32_e32 v14, v14, v84
	v_add_f32_e32 v15, v15, v85
	v_add_f32_e32 v14, v14, v86
	v_add_f32_e32 v15, v15, v87
	v_cvt_pk_bf16_f32 v112, v80, v81
	v_cvt_pk_bf16_f32 v113, v82, v83
	v_cvt_pk_bf16_f32 v114, v84, v85
	v_cvt_pk_bf16_f32 v115, v86, v87
	s_waitcnt lgkmcnt(6)
	v_mfma_f32_32x32x16_bf16 v[32:47], v[116:119], v[10:13], v[32:47]
	ds_read_b64_tr_b16 v[116:117], v182 offset:38144
	ds_read_b64_tr_b16 v[118:119], v182 offset:39296
	v_exp_f32_e32 v88, v88
	v_exp_f32_e32 v89, v89
	v_exp_f32_e32 v90, v90
	v_exp_f32_e32 v91, v91
	v_exp_f32_e32 v92, v92
	v_exp_f32_e32 v93, v93
	v_exp_f32_e32 v94, v94
	v_exp_f32_e32 v95, v95
	v_add_f32_e32 v14, v14, v88
	v_add_f32_e32 v15, v15, v89
	s_waitcnt lgkmcnt(6)
	v_mfma_f32_32x32x16_bf16 v[16:31], v[120:123], v[10:13], v[16:31]
	ds_read_b64_tr_b16 v[120:121], v182 offset:38208
	ds_read_b64_tr_b16 v[122:123], v182 offset:39360
	v_add_f32_e32 v14, v14, v90
	v_add_f32_e32 v15, v15, v91
	v_add_f32_e32 v14, v14, v92
	v_add_f32_e32 v15, v15, v93
	v_add_f32_e32 v14, v14, v94
	v_add_f32_e32 v15, v15, v95
	v_cvt_pk_bf16_f32 v124, v88, v89
	v_cvt_pk_bf16_f32 v125, v90, v91
	v_cvt_pk_bf16_f32 v126, v92, v93
	v_cvt_pk_bf16_f32 v127, v94, v95
	s_waitcnt lgkmcnt(6)
	v_mfma_f32_32x32x16_bf16 v[32:47], v[2:5], v[112:115], v[32:47]
	ds_read_b64_tr_b16 v[2:3], v182 offset:40448
	ds_read_b64_tr_b16 v[4:5], v182 offset:41600
	v_exp_f32_e32 v64, v64
	v_exp_f32_e32 v65, v65
	v_exp_f32_e32 v66, v66
	v_exp_f32_e32 v67, v67
	v_exp_f32_e32 v68, v68
	v_exp_f32_e32 v69, v69
	v_exp_f32_e32 v70, v70
	v_exp_f32_e32 v71, v71
	v_add_f32_e32 v14, v14, v64
	v_add_f32_e32 v15, v15, v65
	s_waitcnt lgkmcnt(6)
	v_mfma_f32_32x32x16_bf16 v[16:31], v[6:9], v[112:115], v[16:31]
	ds_read_b64_tr_b16 v[6:7], v182 offset:40512
	ds_read_b64_tr_b16 v[8:9], v182 offset:41664
	v_add_f32_e32 v14, v14, v66
	v_add_f32_e32 v15, v15, v67
	v_add_f32_e32 v14, v14, v68
	v_add_f32_e32 v15, v15, v69
	v_add_f32_e32 v14, v14, v70
	v_add_f32_e32 v15, v15, v71
	v_cvt_pk_bf16_f32 v10, v64, v65
	v_cvt_pk_bf16_f32 v11, v66, v67
	v_cvt_pk_bf16_f32 v12, v68, v69
	v_cvt_pk_bf16_f32 v13, v70, v71
	s_waitcnt lgkmcnt(6)
	v_mfma_f32_32x32x16_bf16 v[32:47], v[116:119], v[124:127], v[32:47]
	ds_read_b64_tr_b16 v[116:117], v182 offset:42752
	ds_read_b64_tr_b16 v[118:119], v182 offset:43904
	v_exp_f32_e32 v72, v72
	v_exp_f32_e32 v73, v73
	v_exp_f32_e32 v74, v74
	v_exp_f32_e32 v75, v75
	v_exp_f32_e32 v76, v76
	v_exp_f32_e32 v77, v77
	v_exp_f32_e32 v78, v78
	v_exp_f32_e32 v79, v79
	v_add_f32_e32 v14, v14, v72
	v_add_f32_e32 v15, v15, v73
	s_waitcnt lgkmcnt(6)
	v_mfma_f32_32x32x16_bf16 v[16:31], v[120:123], v[124:127], v[16:31]
	ds_read_b64_tr_b16 v[120:121], v182 offset:42816
	ds_read_b64_tr_b16 v[122:123], v182 offset:43968
	v_add_f32_e32 v14, v14, v74
	v_add_f32_e32 v15, v15, v75
	v_add_f32_e32 v14, v14, v76
	v_add_f32_e32 v15, v15, v77
	v_add_f32_e32 v14, v14, v78
	v_add_f32_e32 v15, v15, v79
	v_cvt_pk_bf16_f32 v112, v72, v73
	v_cvt_pk_bf16_f32 v113, v74, v75
	v_cvt_pk_bf16_f32 v114, v76, v77
	v_cvt_pk_bf16_f32 v115, v78, v79
	s_nop 0
	s_waitcnt lgkmcnt(6)
	v_mfma_f32_32x32x16_bf16 v[32:47], v[2:5], v[10:13], v[32:47]
	v_add_f32_e32 v14, v14, v15
	s_waitcnt lgkmcnt(4)
	v_mfma_f32_32x32x16_bf16 v[16:31], v[6:9], v[10:13], v[16:31]
	v_add_f32_e32 v0, v0, v14
	s_waitcnt lgkmcnt(2)
	v_mfma_f32_32x32x16_bf16 v[32:47], v[116:119], v[112:115], v[32:47]
	s_waitcnt lgkmcnt(0)
	v_mfma_f32_32x32x16_bf16 v[16:31], v[120:123], v[112:115], v[16:31]
	s_branch .LBB1_884
